# dilated-attention decoder units rotated by 8 per round so every CU sees every unit type equally often; no s_setprio flips in GEMM loops; barrier v4
# baseline (speedup 1.0000x reference)
.LBB0_178:
	s_cmpk_lt_i32 s96, 0xc00
	s_cselect_b64 s[2:3], -1, 0
	s_cmpk_gt_i32 s96, 0xbff
	s_mov_b64 s[4:5], -1
	s_cbranch_scc0 .LBB0_187
	s_and_b32 s19, s96, 31
	s_add_i32 s8, s96, 0xfffff400
	s_lshr_b32 s8, s8, 8
	s_lshl_b32 s8, s8, 3
	s_add_i32 s19, s19, s8
	s_and_b32 s19, s19, 31
	s_cmp_lt_u32 s19, 8
	s_mov_b32 s16, 0
	s_cbranch_scc1 .LBB0_184
	s_cmp_gt_u32 s19, 15
	s_cbranch_scc0 .LBB0_182
	s_add_i32 s6, s19, -16
	s_mov_b64 s[4:5], 0
